# MLA and mLSTM loops: s_setprio 1 around QK and PV MFMA sections
# baseline (speedup 1.0000x reference)
; #define SBAR() __builtin_amdgcn_sched_barrier(0)
; template <int MODE> __device__ __forceinline__ void partialSM(f32x16& p0, f32x16& p1, float& m_reg, float& mn, float& alpha, float C, float thr, const float* auxk, float pq, float nsl, int hi) {
;     ...
;   float pmax = p0[0];
; #pragma unroll
;   for (int r = 1; r < 16; ++r) pmax = fmaxf(pmax, p0[r]);
; #pragma unroll
;   for (int r = 0; r < 16; ++r) pmax = fmaxf(pmax, p1[r]);
;   { auto rr = __builtin_amdgcn_permlane32_swap(__float_as_uint(pmax), __float_as_uint(pmax), false, false);
;     pmax = fmaxf(__uint_as_float(rr[0]), __uint_as_float(rr[1])); }
;   if (__builtin_expect(__all(pmax - m_reg <= thr), 1)) { mn = m_reg; alpha = 1.f; }
;   else { mn = fmaxf(m_reg, pmax); alpha = __builtin_amdgcn_exp2f((m_reg - mn) * C); m_reg = mn; }
;     ...
;   const int sw = (r32 & 7) << 4; const char* k0p = Ks + r32 * ROWB; const char* k1p = Ks + (32 + r32) * ROWB;
; #pragma unroll
;   for (int h2 = 0; h2 < DQK / 32; ++h2) { const int cba = (((2 * h2) * 16 + hi * 8) * 2) ^ sw, cbb = (((2 * h2 + 1) * 16 + hi * 8) * 2) ^ sw;
;     const bf16x8 a0 = *reinterpret_cast<const bf16x8*>(k0p + cba), a1 = *reinterpret_cast<const bf16x8*>(k1p + cba);
;     const bf16x8 b0 = *reinterpret_cast<const bf16x8*>(k0p + cbb), b1 = *reinterpret_cast<const bf16x8*>(k1p + cbb);
;     SBAR();
;     p0 = __builtin_amdgcn_mfma_f32_32x32x16_bf16(a0, qr[2 * h2], p0, 0, 0, 0);
;     p1 = __builtin_amdgcn_mfma_f32_32x32x16_bf16(a1, qr[2 * h2], p1, 0, 0, 0);
;     p0 = __builtin_amdgcn_mfma_f32_32x32x16_bf16(b0, qr[2 * h2 + 1], p0, 0, 0, 0);
;     p1 = __builtin_amdgcn_mfma_f32_32x32x16_bf16(b1, qr[2 * h2 + 1], p1, 0, 0, 0);
;     SBAR(); }
.LBB0_1020:
	s_setprio 1
	s_mul_i32 s4, s68, 0x6000
	v_add_u32_e32 v192, s4, v159
	v_add_u32_e32 v210, v192, v161
	v_add_u32_e32 v211, v192, v162
	ds_read_b128 v[176:179], v210 offset:49152
	ds_read_b128 v[180:183], v210 offset:61440
	ds_read_b128 v[184:187], v211 offset:49152
	ds_read_b128 v[188:191], v211 offset:61440
	v_add_u32_e32 v210, v192, v163
	v_add_u32_e32 v211, v192, v164
	ds_read_b128 v[194:197], v210 offset:49152
	ds_read_b128 v[198:201], v210 offset:61440
	ds_read_b128 v[202:205], v211 offset:49152
	ds_read_b128 v[206:209], v211 offset:61440
	s_waitcnt lgkmcnt(4)
	v_mfma_f32_32x32x16_bf16 v[82:97], v[176:179], v[98:101], 0
	v_mfma_f32_32x32x16_bf16 v[66:81], v[180:183], v[98:101], 0
	v_mfma_f32_32x32x16_bf16 v[82:97], v[184:187], v[102:105], v[82:97]
	v_mfma_f32_32x32x16_bf16 v[66:81], v[188:191], v[102:105], v[66:81]
	v_add_u32_e32 v210, v192, v165
	v_add_u32_e32 v211, v192, v166
	ds_read_b128 v[176:179], v210 offset:49152
	ds_read_b128 v[180:183], v210 offset:61440
	ds_read_b128 v[184:187], v211 offset:49152
	ds_read_b128 v[188:191], v211 offset:61440
	s_waitcnt lgkmcnt(4)
	v_mfma_f32_32x32x16_bf16 v[82:97], v[194:197], v[106:109], v[82:97]
	v_mfma_f32_32x32x16_bf16 v[66:81], v[198:201], v[106:109], v[66:81]
	v_mfma_f32_32x32x16_bf16 v[82:97], v[202:205], v[110:113], v[82:97]
	v_mfma_f32_32x32x16_bf16 v[66:81], v[206:209], v[110:113], v[66:81]
	v_add_u32_e32 v210, v192, v167
	v_add_u32_e32 v211, v192, v168
	ds_read_b128 v[194:197], v210 offset:49152
	ds_read_b128 v[198:201], v210 offset:61440
	ds_read_b128 v[202:205], v211 offset:49152
	ds_read_b128 v[206:209], v211 offset:61440
	s_waitcnt lgkmcnt(4)
	v_mfma_f32_32x32x16_bf16 v[82:97], v[176:179], v[114:117], v[82:97]
	v_mfma_f32_32x32x16_bf16 v[66:81], v[180:183], v[114:117], v[66:81]
	v_mfma_f32_32x32x16_bf16 v[82:97], v[184:187], v[118:121], v[82:97]
	v_mfma_f32_32x32x16_bf16 v[66:81], v[188:191], v[118:121], v[66:81]
	v_add_u32_e32 v210, v192, v169
	v_add_u32_e32 v211, v192, v171
	ds_read_b128 v[176:179], v210 offset:49152
	ds_read_b128 v[180:183], v210 offset:61440
	ds_read_b128 v[184:187], v211 offset:49152
	ds_read_b128 v[188:191], v211 offset:61440
	s_waitcnt lgkmcnt(4)
	v_mfma_f32_32x32x16_bf16 v[82:97], v[194:197], v[122:125], v[82:97]
	v_mfma_f32_32x32x16_bf16 v[66:81], v[198:201], v[122:125], v[66:81]
	v_mfma_f32_32x32x16_bf16 v[82:97], v[202:205], v[126:129], v[82:97]
	v_mfma_f32_32x32x16_bf16 v[66:81], v[206:209], v[126:129], v[66:81]
	v_add_u32_e32 v210, v192, v172
	v_add_u32_e32 v211, v192, v173
	ds_read_b128 v[194:197], v210 offset:49152
	ds_read_b128 v[198:201], v210 offset:61440
	ds_read_b128 v[202:205], v211 offset:49152
	ds_read_b128 v[206:209], v211 offset:61440
	s_waitcnt lgkmcnt(4)
	v_mfma_f32_32x32x16_bf16 v[82:97], v[176:179], v[130:133], v[82:97]
	v_mfma_f32_32x32x16_bf16 v[66:81], v[180:183], v[130:133], v[66:81]
	v_mfma_f32_32x32x16_bf16 v[82:97], v[184:187], v[134:137], v[82:97]
	v_mfma_f32_32x32x16_bf16 v[66:81], v[188:191], v[134:137], v[66:81]
	s_waitcnt lgkmcnt(0)
	v_mfma_f32_32x32x16_bf16 v[82:97], v[194:197], v[138:141], v[82:97]
	v_mfma_f32_32x32x16_bf16 v[66:81], v[198:201], v[138:141], v[66:81]
	v_mfma_f32_32x32x16_bf16 v[82:97], v[202:205], v[142:145], v[82:97]
	v_mfma_f32_32x32x16_bf16 v[66:81], v[206:209], v[142:145], v[66:81]
	s_setprio 0
	s_nop 10
	v_max_f32_e32 v176, v83, v83
	v_max_f32_e32 v177, v82, v82
	v_max_f32_e32 v176, v177, v176
	v_max3_f32 v176, v176, v84, v85
	v_max3_f32 v176, v176, v86, v87
	v_max3_f32 v176, v176, v88, v89
	v_max3_f32 v176, v176, v90, v91
	v_max3_f32 v176, v176, v92, v93
	v_max3_f32 v176, v176, v94, v95
	v_max3_f32 v176, v176, v96, v97
	v_max3_f32 v176, v176, v66, v67
	v_max3_f32 v176, v176, v68, v69
	v_max3_f32 v176, v176, v70, v71
	v_max3_f32 v176, v176, v72, v73
	v_max3_f32 v176, v176, v74, v75
	v_max3_f32 v176, v176, v76, v77
	v_max3_f32 v176, v176, v78, v79
	v_max3_f32 v176, v176, v80, v81
	v_mov_b32_e32 v177, v176
	s_nop 1
	v_permlane32_swap_b32_e32 v176, v177
	v_max_f32_e32 v177, v177, v177
	v_max_f32_e32 v176, v176, v176
	v_max_f32_e32 v176, v176, v177
	v_sub_f32_e32 v177, v176, v175
	s_mov_b32 s4, 0x42ddb3d8
	v_cmp_ge_f32_e32 vcc, s4, v177
	v_max_f32_e32 v177, v175, v175
	v_max_f32_e32 v177, v177, v176
	v_sub_f32_e32 v176, v175, v177
	v_mul_f32_e32 v176, 0x3dd53b94, v176
	v_exp_f32_e32 v176, v176
	s_cmp_eq_u64 vcc, exec
	s_cselect_b64 s[4:5], -1, 0
	v_cndmask_b32_e64 v176, v176, 1.0, s[4:5]
	v_cmp_gt_f32_e32 vcc, 1.0, v176
	s_cbranch_vccz .LBB0_1024
	s_and_saveexec_b64 s[38:39], s[2:3]
	ds_write_b32 v170, v176 offset:128
	s_or_b64 exec, exec, s[38:39]
	s_waitcnt lgkmcnt(0)
	v_add_u32_e32 v190, s63, v160
	ds_read_b128 v[178:181], v190 offset:224
	ds_read_b128 v[182:185], v190 offset:192
	ds_read_b128 v[186:189], v190 offset:160
	ds_read_b128 v[190:193], v190 offset:128
	s_waitcnt lgkmcnt(3)
	v_pk_mul_f32 v[62:63], v[62:63], v[178:179]
	s_waitcnt lgkmcnt(2)
	v_pk_mul_f32 v[58:59], v[58:59], v[182:183]
	s_waitcnt lgkmcnt(1)
	v_pk_mul_f32 v[54:55], v[54:55], v[186:187]
	v_pk_mul_f32 v[64:65], v[64:65], v[180:181]
	v_pk_mul_f32 v[60:61], v[60:61], v[184:185]
	v_pk_mul_f32 v[56:57], v[56:57], v[188:189]
	s_waitcnt lgkmcnt(0)
	v_pk_mul_f32 v[52:53], v[52:53], v[192:193]
	v_pk_mul_f32 v[50:51], v[50:51], v[190:191]
	v_pk_mul_f32 v[46:47], v[46:47], v[178:179]
	v_pk_mul_f32 v[42:43], v[42:43], v[182:183]
	v_pk_mul_f32 v[38:39], v[38:39], v[186:187]
	v_pk_mul_f32 v[48:49], v[48:49], v[180:181]
	v_pk_mul_f32 v[44:45], v[44:45], v[184:185]
	v_pk_mul_f32 v[40:41], v[40:41], v[188:189]
	v_pk_mul_f32 v[36:37], v[36:37], v[192:193]
	v_pk_mul_f32 v[34:35], v[34:35], v[190:191]
	v_pk_mul_f32 v[30:31], v[30:31], v[178:179]
	v_pk_mul_f32 v[26:27], v[26:27], v[182:183]
	v_pk_mul_f32 v[22:23], v[22:23], v[186:187]
	v_pk_mul_f32 v[32:33], v[32:33], v[180:181]
	v_pk_mul_f32 v[28:29], v[28:29], v[184:185]
	v_pk_mul_f32 v[24:25], v[24:25], v[188:189]
	v_pk_mul_f32 v[20:21], v[20:21], v[192:193]
	v_pk_mul_f32 v[18:19], v[18:19], v[190:191]
	v_pk_mul_f32 v[14:15], v[14:15], v[178:179]
	v_pk_mul_f32 v[10:11], v[10:11], v[182:183]
	v_pk_mul_f32 v[6:7], v[6:7], v[186:187]
	v_pk_mul_f32 v[16:17], v[16:17], v[180:181]
	v_pk_mul_f32 v[12:13], v[12:13], v[184:185]
	v_pk_mul_f32 v[8:9], v[8:9], v[188:189]
	v_pk_mul_f32 v[4:5], v[4:5], v[192:193]
	v_pk_mul_f32 v[2:3], v[2:3], v[190:191]
; #define SBAR() __builtin_amdgcn_sched_barrier(0)
; template <int D0> __device__ __forceinline__ void pv_one(f32x16& od, int vb, bf16x8 pa0, bf16x8 pa1, bf16x8 pa2, bf16x8 pa3) {
;   const s16x4 l0 = tr_read<v_rd_off(D0, 0, 0)>(vb), h0 = tr_read<v_rd_off(D0, 0, 1)>(vb), l1 = tr_read<v_rd_off(D0, 1, 0)>(vb), h1 = tr_read<v_rd_off(D0, 1, 1)>(vb);
;   const s16x4 l2 = tr_read<v_rd_off(D0, 2, 0)>(vb), h2 = tr_read<v_rd_off(D0, 2, 1)>(vb), l3 = tr_read<v_rd_off(D0, 3, 0)>(vb), h3 = tr_read<v_rd_off(D0, 3, 1)>(vb);
;   asm volatile("s_waitcnt lgkmcnt(0)" ::: "memory"); SBAR();
;     ...
;   od = __builtin_amdgcn_mfma_f32_32x32x16_bf16(pa0, PK(l0, h0), od, 0, 0, 0);
;   od = __builtin_amdgcn_mfma_f32_32x32x16_bf16(pa1, PK(l1, h1), od, 0, 0, 0);
;   od = __builtin_amdgcn_mfma_f32_32x32x16_bf16(pa2, PK(l2, h2), od, 0, 0, 0);
;   od = __builtin_amdgcn_mfma_f32_32x32x16_bf16(pa3, PK(l3, h3), od, 0, 0, 0);
;     ...
; }
; __device__ __forceinline__ void pv_d0(f32x16* o, int vb, bf16x8 pa0, bf16x8 pa1, bf16x8 pa2, bf16x8 pa3) {
;   pv_one<0>(o[0], vb, pa0, pa1, pa2, pa3); pv_one<1>(o[1], vb, pa0, pa1, pa2, pa3); pv_one<2>(o[2], vb, pa0, pa1, pa2, pa3); pv_one<3>(o[3], vb, pa0, pa1, pa2, pa3);
; template <int MODE> __device__ __forceinline__ void partialSM(f32x16& p0, f32x16& p1, float& m_reg, float& mn, float& alpha, float C, float thr, const float* auxk, float pq, float nsl, int hi) {
;     ...
;   const float mnC = -mn * C;
; #pragma unroll
;   for (int r = 0; r < 16; ++r) p0[r] = fmaf(p0[r], C, mnC);
; #pragma unroll
;   for (int r = 0; r < 16; ++r) p1[r] = fmaf(p1[r], C, mnC);
; #pragma unroll
;   for (int r = 0; r < 16; ++r) p0[r] = __builtin_amdgcn_exp2f(p0[r]);
; }
; __device__ __forceinline__ void finishSM(f32x16& p0, f32x16& p1, float alpha, float& l_reg, bf16x8& pa0, bf16x8& pa1, bf16x8& pa2, bf16x8& pa3) {
; #pragma unroll
;   for (int r = 0; r < 16; ++r) p1[r] = __builtin_amdgcn_exp2f(p1[r]);
;   float ps = 0;
; #pragma unroll
;   for (int r = 0; r < 16; ++r) ps += p0[r];
; #pragma unroll
;   for (int r = 0; r < 16; ++r) ps += p1[r];
;   { auto rr = __builtin_amdgcn_permlane32_swap(__float_as_uint(ps), __float_as_uint(ps), false, false);
;     ps = __uint_as_float(rr[0]) + __uint_as_float(rr[1]); }
;   l_reg = l_reg * alpha + ps;
;   PK4(p0, 0, pa0); PK4(p0, 8, pa1); PK4(p1, 0, pa2); PK4(p1, 8, pa3);
; }
.LBB0_1024:
	v_cndmask_b32_e64 v175, v177, v175, s[4:5]
	v_mul_f32_e32 v177, 0xbdd53b94, v175
	v_fmamk_f32 v82, v82, 0x3dd53b94, v177
	v_fmamk_f32 v83, v83, 0x3dd53b94, v177
	v_fmamk_f32 v84, v84, 0x3dd53b94, v177
	v_fmamk_f32 v85, v85, 0x3dd53b94, v177
	v_fmamk_f32 v86, v86, 0x3dd53b94, v177
	v_fmamk_f32 v87, v87, 0x3dd53b94, v177
	v_fmamk_f32 v88, v88, 0x3dd53b94, v177
	v_fmamk_f32 v89, v89, 0x3dd53b94, v177
	v_fmamk_f32 v90, v90, 0x3dd53b94, v177
	v_fmamk_f32 v91, v91, 0x3dd53b94, v177
	v_fmamk_f32 v92, v92, 0x3dd53b94, v177
	v_fmamk_f32 v93, v93, 0x3dd53b94, v177
	v_fmamk_f32 v94, v94, 0x3dd53b94, v177
	v_fmamk_f32 v95, v95, 0x3dd53b94, v177
	v_fmamk_f32 v96, v96, 0x3dd53b94, v177
	v_fmamk_f32 v97, v97, 0x3dd53b94, v177
	v_fmamk_f32 v66, v66, 0x3dd53b94, v177
	v_fmamk_f32 v67, v67, 0x3dd53b94, v177
	v_fmamk_f32 v68, v68, 0x3dd53b94, v177
	v_fmamk_f32 v69, v69, 0x3dd53b94, v177
	v_fmamk_f32 v70, v70, 0x3dd53b94, v177
	v_fmamk_f32 v71, v71, 0x3dd53b94, v177
	v_fmamk_f32 v72, v72, 0x3dd53b94, v177
	v_fmamk_f32 v73, v73, 0x3dd53b94, v177
	v_fmamk_f32 v74, v74, 0x3dd53b94, v177
	v_fmamk_f32 v75, v75, 0x3dd53b94, v177
	v_fmamk_f32 v76, v76, 0x3dd53b94, v177
	v_fmamk_f32 v77, v77, 0x3dd53b94, v177
	v_fmamk_f32 v78, v78, 0x3dd53b94, v177
	v_fmamk_f32 v79, v79, 0x3dd53b94, v177
	v_fmamk_f32 v80, v80, 0x3dd53b94, v177
	v_fmac_f32_e32 v177, 0x3dd53b94, v81
	v_exp_f32_e32 v81, v82
	v_exp_f32_e32 v82, v83
	v_exp_f32_e32 v83, v84
	v_exp_f32_e32 v84, v85
	v_exp_f32_e32 v85, v86
	v_exp_f32_e32 v86, v87
	v_exp_f32_e32 v87, v88
	v_exp_f32_e32 v88, v89
	v_exp_f32_e32 v89, v90
	v_exp_f32_e32 v90, v91
	v_exp_f32_e32 v91, v92
	v_exp_f32_e32 v92, v93
	v_exp_f32_e32 v93, v94
	v_exp_f32_e32 v94, v95
	v_exp_f32_e32 v95, v96
	v_exp_f32_e32 v96, v97
	v_exp_f32_e32 v97, v66
	v_add_f32_e32 v66, 0, v81
	v_add_f32_e32 v66, v82, v66
	v_add_f32_e32 v66, v83, v66
	v_add_f32_e32 v66, v84, v66
	v_add_f32_e32 v66, v85, v66
	v_add_f32_e32 v66, v86, v66
	v_add_f32_e32 v66, v87, v66
	v_add_f32_e32 v66, v88, v66
	v_add_f32_e32 v66, v89, v66
	v_add_f32_e32 v66, v90, v66
	v_add_f32_e32 v66, v91, v66
	v_add_f32_e32 v66, v92, v66
	v_add_f32_e32 v66, v93, v66
	v_exp_f32_e32 v178, v67
	v_add_f32_e32 v66, v94, v66
	v_exp_f32_e32 v179, v68
	v_add_f32_e32 v66, v95, v66
	v_exp_f32_e32 v180, v69
	v_add_f32_e32 v66, v96, v66
	v_exp_f32_e32 v181, v70
	v_add_f32_e32 v66, v97, v66
	v_exp_f32_e32 v182, v71
	v_add_f32_e32 v66, v178, v66
	v_exp_f32_e32 v183, v72
	v_add_f32_e32 v66, v179, v66
	v_exp_f32_e32 v184, v73
	v_add_f32_e32 v66, v180, v66
	v_exp_f32_e32 v185, v74
	v_add_f32_e32 v66, v181, v66
	v_exp_f32_e32 v186, v75
	v_add_f32_e32 v66, v182, v66
	v_exp_f32_e32 v187, v76
	v_add_f32_e32 v66, v183, v66
	v_exp_f32_e32 v188, v77
	v_add_f32_e32 v66, v184, v66
	v_exp_f32_e32 v189, v78
	v_add_f32_e32 v66, v185, v66
	v_exp_f32_e32 v190, v79
	v_add_f32_e32 v66, v186, v66
	v_exp_f32_e32 v191, v80
	v_add_f32_e32 v66, v187, v66
	v_exp_f32_e32 v177, v177
	v_add_f32_e32 v66, v188, v66
	v_add_f32_e32 v66, v189, v66
	v_add_f32_e32 v66, v190, v66
	v_add_f32_e32 v66, v191, v66
	v_add_f32_e32 v66, v177, v66
	v_mov_b32_e32 v67, v66
	s_nop 1
	v_permlane32_swap_b32_e32 v66, v67
	v_cvt_pk_bf16_f32 v68, v81, v82
	v_cvt_pk_bf16_f32 v69, v83, v84
	v_cvt_pk_bf16_f32 v70, v85, v86
	v_cvt_pk_bf16_f32 v71, v87, v88
	v_cvt_pk_bf16_f32 v72, v89, v90
	v_cvt_pk_bf16_f32 v73, v91, v92
	v_cvt_pk_bf16_f32 v74, v93, v94
	v_cvt_pk_bf16_f32 v75, v95, v96
	v_cvt_pk_bf16_f32 v76, v97, v178
	v_cvt_pk_bf16_f32 v77, v179, v180
	v_cvt_pk_bf16_f32 v78, v181, v182
	v_cvt_pk_bf16_f32 v79, v183, v184
	v_cvt_pk_bf16_f32 v80, v185, v186
	v_cvt_pk_bf16_f32 v81, v187, v188
	v_cvt_pk_bf16_f32 v82, v189, v190
	v_cvt_pk_bf16_f32 v83, v191, v177
	v_permlane32_swap_b32_e32 v68, v70
	v_permlane32_swap_b32_e32 v69, v71
	v_permlane32_swap_b32_e32 v72, v74
	v_permlane32_swap_b32_e32 v73, v75
	v_permlane32_swap_b32_e32 v76, v78
	v_permlane32_swap_b32_e32 v77, v79
	v_permlane32_swap_b32_e32 v80, v82
	v_permlane32_swap_b32_e32 v81, v83
	v_lshl_add_u32 v96, s68, 14, v174
	ds_read_b64_tr_b16 v[84:85], v96 offset:0
	ds_read_b64_tr_b16 v[86:87], v96 offset:0x800
	ds_read_b64_tr_b16 v[88:89], v96 offset:0x1000
	ds_read_b64_tr_b16 v[90:91], v96 offset:0x1800
	ds_read_b64_tr_b16 v[92:93], v96 offset:0x2000
	ds_read_b64_tr_b16 v[94:95], v96 offset:0x2800
	ds_read_b64_tr_b16 v[178:179], v96 offset:0x3000
	ds_read_b64_tr_b16 v[180:181], v96 offset:0x3800
	s_waitcnt lgkmcnt(0)
	s_nop 0
	s_setprio 1
	v_mfma_f32_32x32x16_bf16 v[50:65], v[68:71], v[84:87], v[50:65]
	ds_read_b64_tr_b16 v[84:85], v96 offset:0x200
	ds_read_b64_tr_b16 v[86:87], v96 offset:0xa00
	v_mfma_f32_32x32x16_bf16 v[50:65], v[72:75], v[88:91], v[50:65]
	ds_read_b64_tr_b16 v[88:89], v96 offset:0x1200
	ds_read_b64_tr_b16 v[90:91], v96 offset:0x1a00
	v_mfma_f32_32x32x16_bf16 v[50:65], v[76:79], v[92:95], v[50:65]
	ds_read_b64_tr_b16 v[92:93], v96 offset:0x2200
	ds_read_b64_tr_b16 v[94:95], v96 offset:0x2a00
	v_mfma_f32_32x32x16_bf16 v[50:65], v[80:83], v[178:181], v[50:65]
	ds_read_b64_tr_b16 v[178:179], v96 offset:0x3200
	ds_read_b64_tr_b16 v[180:181], v96 offset:0x3a00
	s_waitcnt lgkmcnt(0)
	v_mfma_f32_32x32x16_bf16 v[34:49], v[68:71], v[84:87], v[34:49]
	ds_read_b64_tr_b16 v[84:85], v96 offset:0x400
	ds_read_b64_tr_b16 v[86:87], v96 offset:0xc00
	v_mfma_f32_32x32x16_bf16 v[34:49], v[72:75], v[88:91], v[34:49]
	ds_read_b64_tr_b16 v[88:89], v96 offset:0x1400
	ds_read_b64_tr_b16 v[90:91], v96 offset:0x1c00
	v_mfma_f32_32x32x16_bf16 v[34:49], v[76:79], v[92:95], v[34:49]
	ds_read_b64_tr_b16 v[92:93], v96 offset:0x2400
	ds_read_b64_tr_b16 v[94:95], v96 offset:0x2c00
	v_mfma_f32_32x32x16_bf16 v[34:49], v[80:83], v[178:181], v[34:49]
	ds_read_b64_tr_b16 v[178:179], v96 offset:0x3400
	ds_read_b64_tr_b16 v[180:181], v96 offset:0x3c00
	s_waitcnt lgkmcnt(0)
	v_mfma_f32_32x32x16_bf16 v[18:33], v[68:71], v[84:87], v[18:33]
	ds_read_b64_tr_b16 v[84:85], v96 offset:0x600
	ds_read_b64_tr_b16 v[86:87], v96 offset:0xe00
	v_mfma_f32_32x32x16_bf16 v[18:33], v[72:75], v[88:91], v[18:33]
	ds_read_b64_tr_b16 v[88:89], v96 offset:0x1600
	ds_read_b64_tr_b16 v[90:91], v96 offset:0x1e00
	v_mfma_f32_32x32x16_bf16 v[18:33], v[76:79], v[92:95], v[18:33]
	ds_read_b64_tr_b16 v[92:93], v96 offset:0x2600
	ds_read_b64_tr_b16 v[94:95], v96 offset:0x2e00
	v_mfma_f32_32x32x16_bf16 v[18:33], v[80:83], v[178:181], v[18:33]
	ds_read_b64_tr_b16 v[178:179], v96 offset:0x3600
	ds_read_b64_tr_b16 v[180:181], v96 offset:0x3e00
	s_waitcnt lgkmcnt(0)
	v_mfma_f32_32x32x16_bf16 v[2:17], v[68:71], v[84:87], v[2:17]
	s_mov_b64 s[4:5], -1
	s_and_b64 vcc, exec, s[56:57]
	v_mfma_f32_32x32x16_bf16 v[2:17], v[72:75], v[88:91], v[2:17]
	v_mfma_f32_32x32x16_bf16 v[2:17], v[76:79], v[92:95], v[2:17]
	v_mfma_f32_32x32x16_bf16 v[2:17], v[80:83], v[178:181], v[2:17]
	s_setprio 0
	s_cbranch_vccz .LBB0_1026
	s_waitcnt vmcnt(0) lgkmcnt(0)
	s_barrier
	s_mov_b64 s[4:5], 0

; #define SBAR() __builtin_amdgcn_sched_barrier(0)
; template <int OFF> __device__ __forceinline__ s16x4 tr_read(int vb) { s16x4 r; asm volatile("ds_read_b64_tr_b16 %0, %1 offset:%2" : "=&v"(r) : "v"(vb), "i"(OFF) : "memory"); return r; }
; __device__ __forceinline__ void finishW(f32x16& p0, f32x16& p1, float& l_reg, bf16x8& pa0, bf16x8& pa1, bf16x8& pa2, bf16x8& pa3) {
;   float ps = 0;
; #pragma unroll
;   for (int r = 0; r < 16; ++r) ps += p0[r];
; #pragma unroll
;   for (int r = 0; r < 16; ++r) ps += p1[r];
;   { auto rr = __builtin_amdgcn_permlane32_swap(__float_as_uint(ps), __float_as_uint(ps), false, false);
;     ps = __uint_as_float(rr[0]) + __uint_as_float(rr[1]); }
;   l_reg += ps;
;   PK4(p0, 0, pa0); PK4(p0, 8, pa1); PK4(p1, 0, pa2); PK4(p1, 8, pa3);
; }
; template <int D0> __device__ __forceinline__ void pv_one_lean(f32x16& od, int vb, bf16x8 pa0, bf16x8 pa1, bf16x8 pa2, bf16x8 pa3) {
;     ...
;   { const s16x4 l0 = tr_read<v_rd_off(D0, 0, 0)>(vb), h0 = tr_read<v_rd_off(D0, 0, 1)>(vb), l1 = tr_read<v_rd_off(D0, 1, 0)>(vb), h1 = tr_read<v_rd_off(D0, 1, 1)>(vb);
;     asm volatile("s_waitcnt lgkmcnt(0)" ::: "memory"); SBAR();
;     od = __builtin_amdgcn_mfma_f32_32x32x16_bf16(pa0, PKL(l0, h0), od, 0, 0, 0); od = __builtin_amdgcn_mfma_f32_32x32x16_bf16(pa1, PKL(l1, h1), od, 0, 0, 0); }
;   SBAR();
;   { const s16x4 l2 = tr_read<v_rd_off(D0, 2, 0)>(vb), h2 = tr_read<v_rd_off(D0, 2, 1)>(vb), l3 = tr_read<v_rd_off(D0, 3, 0)>(vb), h3 = tr_read<v_rd_off(D0, 3, 1)>(vb);
;     asm volatile("s_waitcnt lgkmcnt(0)" ::: "memory"); SBAR();
;     od = __builtin_amdgcn_mfma_f32_32x32x16_bf16(pa2, PKL(l2, h2), od, 0, 0, 0); od = __builtin_amdgcn_mfma_f32_32x32x16_bf16(pa3, PKL(l3, h3), od, 0, 0, 0); }
.LBB0_1040:
	v_add_f32_e32 v136, 0, v196
	v_add_f32_e32 v136, v197, v136
	v_add_f32_e32 v136, v144, v136
	v_add_f32_e32 v136, v145, v136
	v_add_f32_e32 v136, v198, v136
	v_add_f32_e32 v136, v199, v136
	v_add_f32_e32 v136, v200, v136
	v_add_f32_e32 v136, v201, v136
	v_add_f32_e32 v136, v150, v136
	v_add_f32_e32 v136, v151, v136
	v_add_f32_e32 v136, v152, v136
	v_add_f32_e32 v136, v153, v136
	v_add_f32_e32 v136, v202, v136
	v_add_f32_e32 v136, v203, v136
	v_add_f32_e32 v136, v204, v136
	v_add_f32_e32 v136, v205, v136
	v_add_f32_e32 v136, v128, v136
	v_add_f32_e32 v136, v129, v136
	v_add_f32_e32 v136, v130, v136
	v_add_f32_e32 v136, v131, v136
	v_add_f32_e32 v136, v132, v136
	v_add_f32_e32 v136, v133, v136
	v_add_f32_e32 v136, v134, v136
	v_add_f32_e32 v136, v135, v136
	v_add_f32_e32 v136, v146, v136
	v_add_f32_e32 v136, v147, v136
	v_add_f32_e32 v136, v148, v136
	v_add_f32_e32 v136, v149, v136
	v_add_f32_e32 v136, v154, v136
	v_add_f32_e32 v136, v155, v136
	v_add_f32_e32 v136, v156, v136
	v_add_f32_e32 v136, v157, v136
	v_mov_b32_e32 v137, v136
	s_nop 1
	v_permlane32_swap_b32_e32 v136, v137
	v_add_f32_e32 v136, v136, v137
	v_add_f32_e32 v214, v214, v136
	v_cvt_pk_bf16_f32 v136, v196, v197
	v_cvt_pk_bf16_f32 v137, v144, v145
	v_cvt_pk_bf16_f32 v138, v198, v199
	v_cvt_pk_bf16_f32 v139, v200, v201
	v_cvt_pk_bf16_f32 v140, v150, v151
	v_cvt_pk_bf16_f32 v141, v152, v153
	v_cvt_pk_bf16_f32 v142, v202, v203
	v_cvt_pk_bf16_f32 v143, v204, v205
	v_cvt_pk_bf16_f32 v128, v128, v129
	v_cvt_pk_bf16_f32 v129, v130, v131
	v_cvt_pk_bf16_f32 v130, v132, v133
	v_cvt_pk_bf16_f32 v131, v134, v135
	v_cvt_pk_bf16_f32 v132, v146, v147
	v_cvt_pk_bf16_f32 v133, v148, v149
	v_cvt_pk_bf16_f32 v134, v154, v155
	v_cvt_pk_bf16_f32 v135, v156, v157
	v_permlane32_swap_b32_e32 v136, v138
	v_permlane32_swap_b32_e32 v137, v139
	v_permlane32_swap_b32_e32 v140, v142
	v_permlane32_swap_b32_e32 v141, v143
	v_permlane32_swap_b32_e32 v128, v130
	v_permlane32_swap_b32_e32 v129, v131
	v_permlane32_swap_b32_e32 v132, v134
	v_permlane32_swap_b32_e32 v133, v135
	s_setprio 1
	v_lshl_add_u32 v152, s87, 15, v221
	ds_read_b64_tr_b16 v[144:145], v152 offset:0
	ds_read_b64_tr_b16 v[146:147], v152 offset:0x800
	ds_read_b64_tr_b16 v[148:149], v152 offset:0x1000
	ds_read_b64_tr_b16 v[150:151], v152 offset:0x1800
	ds_read_b64_tr_b16 v[228:229], v152 offset:0x2000
	ds_read_b64_tr_b16 v[230:231], v152 offset:0x2800
	ds_read_b64_tr_b16 v[232:233], v152 offset:0x3000
	ds_read_b64_tr_b16 v[234:235], v152 offset:0x3800
	s_waitcnt lgkmcnt(4)
	v_mfma_f32_32x32x16_bf16 v[112:127], v[136:139], v[144:147], v[112:127]
	v_mfma_f32_32x32x16_bf16 v[112:127], v[140:143], v[148:151], v[112:127]
	ds_read_b64_tr_b16 v[144:145], v152 offset:0x200
	ds_read_b64_tr_b16 v[146:147], v152 offset:0xa00
	ds_read_b64_tr_b16 v[148:149], v152 offset:0x1200
	ds_read_b64_tr_b16 v[150:151], v152 offset:0x1a00
	s_waitcnt lgkmcnt(4)
	v_mfma_f32_32x32x16_bf16 v[112:127], v[128:131], v[228:231], v[112:127]
	v_mfma_f32_32x32x16_bf16 v[112:127], v[132:135], v[232:235], v[112:127]
	ds_read_b64_tr_b16 v[228:229], v152 offset:0x2200
	ds_read_b64_tr_b16 v[230:231], v152 offset:0x2a00
	ds_read_b64_tr_b16 v[232:233], v152 offset:0x3200
	ds_read_b64_tr_b16 v[234:235], v152 offset:0x3a00
	s_waitcnt lgkmcnt(4)
	v_mfma_f32_32x32x16_bf16 v[96:111], v[136:139], v[144:147], v[96:111]
	v_mfma_f32_32x32x16_bf16 v[96:111], v[140:143], v[148:151], v[96:111]
	ds_read_b64_tr_b16 v[144:145], v152 offset:0x400
	ds_read_b64_tr_b16 v[146:147], v152 offset:0xc00
	ds_read_b64_tr_b16 v[148:149], v152 offset:0x1400
	ds_read_b64_tr_b16 v[150:151], v152 offset:0x1c00
	s_waitcnt lgkmcnt(4)
	v_mfma_f32_32x32x16_bf16 v[96:111], v[128:131], v[228:231], v[96:111]
	v_mfma_f32_32x32x16_bf16 v[96:111], v[132:135], v[232:235], v[96:111]
	ds_read_b64_tr_b16 v[228:229], v152 offset:0x2400
	ds_read_b64_tr_b16 v[230:231], v152 offset:0x2c00
	ds_read_b64_tr_b16 v[232:233], v152 offset:0x3400
	ds_read_b64_tr_b16 v[234:235], v152 offset:0x3c00
	s_waitcnt lgkmcnt(4)
; #define SBAR() __builtin_amdgcn_sched_barrier(0)
; template <int OFF> __device__ __forceinline__ s16x4 tr_read(int vb) { s16x4 r; asm volatile("ds_read_b64_tr_b16 %0, %1 offset:%2" : "=&v"(r) : "v"(vb), "i"(OFF) : "memory"); return r; }
; #define WAIT_BAR_0() asm volatile("s_waitcnt vmcnt(0) lgkmcnt(0)\n\ts_barrier" ::: "memory")
; #define WAIT_BAR_0() asm volatile("s_waitcnt vmcnt(0) lgkmcnt(0)\n\ts_barrier" ::: "memory")
; #define WAIT_BAR_0() asm volatile("s_waitcnt vmcnt(0) lgkmcnt(0)\n\ts_barrier" ::: "memory")
; template <int D0> __device__ __forceinline__ void pv_one_lean(f32x16& od, int vb, bf16x8 pa0, bf16x8 pa1, bf16x8 pa2, bf16x8 pa3) {
;     ...
;   { const s16x4 l0 = tr_read<v_rd_off(D0, 0, 0)>(vb), h0 = tr_read<v_rd_off(D0, 0, 1)>(vb), l1 = tr_read<v_rd_off(D0, 1, 0)>(vb), h1 = tr_read<v_rd_off(D0, 1, 1)>(vb);
;     asm volatile("s_waitcnt lgkmcnt(0)" ::: "memory"); SBAR();
;     od = __builtin_amdgcn_mfma_f32_32x32x16_bf16(pa0, PKL(l0, h0), od, 0, 0, 0); od = __builtin_amdgcn_mfma_f32_32x32x16_bf16(pa1, PKL(l1, h1), od, 0, 0, 0); }
;   SBAR();
;   { const s16x4 l2 = tr_read<v_rd_off(D0, 2, 0)>(vb), h2 = tr_read<v_rd_off(D0, 2, 1)>(vb), l3 = tr_read<v_rd_off(D0, 3, 0)>(vb), h3 = tr_read<v_rd_off(D0, 3, 1)>(vb);
;     asm volatile("s_waitcnt lgkmcnt(0)" ::: "memory"); SBAR();
;     od = __builtin_amdgcn_mfma_f32_32x32x16_bf16(pa2, PKL(l2, h2), od, 0, 0, 0); od = __builtin_amdgcn_mfma_f32_32x32x16_bf16(pa3, PKL(l3, h3), od, 0, 0, 0); }
;     ...
; }
; __device__ __forceinline__ void pv_d0_lean(f32x16* o, int vb, bf16x8 pa0, bf16x8 pa1, bf16x8 pa2, bf16x8 pa3) {
;   pv_one_lean<0>(o[0], vb, pa0, pa1, pa2, pa3); SBAR(); pv_one_lean<1>(o[1], vb, pa0, pa1, pa2, pa3); SBAR(); pv_one_lean<2>(o[2], vb, pa0, pa1, pa2, pa3); SBAR(); pv_one_lean<3>(o[3], vb, pa0, pa1, pa2, pa3);
; }
; template <int MODE>
; __device__ __forceinline__ void attn_unit_ml(const AttnUnit& U, char* lds) {
;     ...
;     finishW(p0, p1, l_reg, pa0, pa1, pa2, pa3); SBAR();
;     pv_d0_lean(o, vb0 + st * SHM_V2, pa0, pa1, pa2, pa3); SBAR();
;     pv_d0_lean(o + 4, vb0 + st * SHM_V2 + 16384, pa0, pa1, pa2, pa3);
;     WAIT_BAR_0();
;   }
	v_mfma_f32_32x32x16_bf16 v[80:95], v[136:139], v[144:147], v[80:95]
	v_mfma_f32_32x32x16_bf16 v[80:95], v[140:143], v[148:151], v[80:95]
	ds_read_b64_tr_b16 v[144:145], v152 offset:0x600
	ds_read_b64_tr_b16 v[146:147], v152 offset:0xe00
	ds_read_b64_tr_b16 v[148:149], v152 offset:0x1600
	ds_read_b64_tr_b16 v[150:151], v152 offset:0x1e00
	s_waitcnt lgkmcnt(4)
	v_mfma_f32_32x32x16_bf16 v[80:95], v[128:131], v[228:231], v[80:95]
	v_mfma_f32_32x32x16_bf16 v[80:95], v[132:135], v[232:235], v[80:95]
	ds_read_b64_tr_b16 v[228:229], v152 offset:0x2600
	ds_read_b64_tr_b16 v[230:231], v152 offset:0x2e00
	ds_read_b64_tr_b16 v[232:233], v152 offset:0x3600
	ds_read_b64_tr_b16 v[234:235], v152 offset:0x3e00
	s_waitcnt lgkmcnt(4)
	v_mfma_f32_32x32x16_bf16 v[64:79], v[136:139], v[144:147], v[64:79]
	v_mfma_f32_32x32x16_bf16 v[64:79], v[140:143], v[148:151], v[64:79]
	v_add_u32_e32 v152, 0x4000, v152
	ds_read_b64_tr_b16 v[144:145], v152 offset:0
	ds_read_b64_tr_b16 v[146:147], v152 offset:0x800
	ds_read_b64_tr_b16 v[148:149], v152 offset:0x1000
	ds_read_b64_tr_b16 v[150:151], v152 offset:0x1800
	s_waitcnt lgkmcnt(4)
	v_mfma_f32_32x32x16_bf16 v[64:79], v[128:131], v[228:231], v[64:79]
	v_mfma_f32_32x32x16_bf16 v[64:79], v[132:135], v[232:235], v[64:79]
	ds_read_b64_tr_b16 v[228:229], v152 offset:0x2000
	ds_read_b64_tr_b16 v[230:231], v152 offset:0x2800
	ds_read_b64_tr_b16 v[232:233], v152 offset:0x3000
	ds_read_b64_tr_b16 v[234:235], v152 offset:0x3800
	s_waitcnt lgkmcnt(4)
	v_mfma_f32_32x32x16_bf16 v[48:63], v[136:139], v[144:147], v[48:63]
	v_mfma_f32_32x32x16_bf16 v[48:63], v[140:143], v[148:151], v[48:63]
	ds_read_b64_tr_b16 v[144:145], v152 offset:0x200
	ds_read_b64_tr_b16 v[146:147], v152 offset:0xa00
	ds_read_b64_tr_b16 v[148:149], v152 offset:0x1200
	ds_read_b64_tr_b16 v[150:151], v152 offset:0x1a00
	s_waitcnt lgkmcnt(4)
	v_mfma_f32_32x32x16_bf16 v[48:63], v[128:131], v[228:231], v[48:63]
	v_mfma_f32_32x32x16_bf16 v[48:63], v[132:135], v[232:235], v[48:63]
	ds_read_b64_tr_b16 v[228:229], v152 offset:0x2200
	ds_read_b64_tr_b16 v[230:231], v152 offset:0x2a00
	ds_read_b64_tr_b16 v[232:233], v152 offset:0x3200
	ds_read_b64_tr_b16 v[234:235], v152 offset:0x3a00
	s_waitcnt lgkmcnt(4)
	v_mfma_f32_32x32x16_bf16 v[32:47], v[136:139], v[144:147], v[32:47]
	v_mfma_f32_32x32x16_bf16 v[32:47], v[140:143], v[148:151], v[32:47]
	ds_read_b64_tr_b16 v[144:145], v152 offset:0x400
	ds_read_b64_tr_b16 v[146:147], v152 offset:0xc00
	ds_read_b64_tr_b16 v[148:149], v152 offset:0x1400
	ds_read_b64_tr_b16 v[150:151], v152 offset:0x1c00
	s_waitcnt lgkmcnt(4)
	v_mfma_f32_32x32x16_bf16 v[32:47], v[128:131], v[228:231], v[32:47]
	v_mfma_f32_32x32x16_bf16 v[32:47], v[132:135], v[232:235], v[32:47]
	ds_read_b64_tr_b16 v[228:229], v152 offset:0x2400
	ds_read_b64_tr_b16 v[230:231], v152 offset:0x2c00
	ds_read_b64_tr_b16 v[232:233], v152 offset:0x3400
	ds_read_b64_tr_b16 v[234:235], v152 offset:0x3c00
	s_waitcnt lgkmcnt(4)
	v_mfma_f32_32x32x16_bf16 v[16:31], v[136:139], v[144:147], v[16:31]
	v_mfma_f32_32x32x16_bf16 v[16:31], v[140:143], v[148:151], v[16:31]
	ds_read_b64_tr_b16 v[144:145], v152 offset:0x600
	ds_read_b64_tr_b16 v[146:147], v152 offset:0xe00
	ds_read_b64_tr_b16 v[148:149], v152 offset:0x1600
	ds_read_b64_tr_b16 v[150:151], v152 offset:0x1e00
	s_waitcnt lgkmcnt(4)
	v_mfma_f32_32x32x16_bf16 v[16:31], v[128:131], v[228:231], v[16:31]
	v_mfma_f32_32x32x16_bf16 v[16:31], v[132:135], v[232:235], v[16:31]
	ds_read_b64_tr_b16 v[228:229], v152 offset:0x2600
	ds_read_b64_tr_b16 v[230:231], v152 offset:0x2e00
	ds_read_b64_tr_b16 v[232:233], v152 offset:0x3600
	ds_read_b64_tr_b16 v[234:235], v152 offset:0x3e00
	s_waitcnt lgkmcnt(4)
	v_mfma_f32_32x32x16_bf16 v[0:15], v[136:139], v[144:147], v[0:15]
	v_mfma_f32_32x32x16_bf16 v[0:15], v[140:143], v[148:151], v[0:15]
	s_waitcnt lgkmcnt(0)
	v_mfma_f32_32x32x16_bf16 v[0:15], v[128:131], v[228:231], v[0:15]
	v_mfma_f32_32x32x16_bf16 v[0:15], v[132:135], v[232:235], v[0:15]
	s_setprio 0
	s_add_i32 s86, s86, 64
	s_add_u32 s58, s58, 0x80000
	s_addc_u32 s59, s59, 0
	s_add_u32 s60, s60, 0x80000
	s_waitcnt vmcnt(0) lgkmcnt(0)
	s_barrier
	s_addc_u32 s61, s61, 0
	s_add_i32 s84, s84, 1
	s_add_i32 s11, s41, s84
	v_add_u32_e32 v222, 0x100, v222
	v_subrev_u32_e32 v223, 64, v223
	s_cmp_eq_u32 s11, 1
	s_cbranch_scc1 .LBB0_1047

; template <int MODE> __device__ __forceinline__ void partialW2(f32x16& p0, f32x16& p1, const float* auxk, bool band, int qrel, int hi) {
; #pragma unroll
;   for (int g = 0; g < 4; ++g) { const f32x4 a = *(const f32x4*)(auxk + 8 * g + 4 * hi), b = *(const f32x4*)(auxk + 32 + 8 * g + 4 * hi);
; #pragma unroll
;     for (int e = 0; e < 4; ++e) { p0[4 * g + e] *= a[e]; p1[4 * g + e] *= b[e]; } }
;   if (band) {
; #pragma unroll
;     for (int r = 0; r < 16; ++r) { const int kvl = (r & 3) + 8 * (r >> 2);
;       const bool k0 = (MODE == 2) ? (kvl <= qrel) : (kvl >= qrel), k1 = (MODE == 2) ? (kvl + 32 <= qrel) : (kvl + 32 >= qrel);
;       p0[r] = k0 ? p0[r] : 0.f; p1[r] = k1 ? p1[r] : 0.f; }
;   }
; }
; template <int DQK> __device__ __forceinline__ void qkt_acc(f32x16& p0, f32x16& p1, const char* Ks, const bf16x8* qr, int r32, int hi) {
;   constexpr int ROWB = DQK * 2;
;   const int sw = (r32 & 7) << 4; const char* k0p = Ks + r32 * ROWB; const char* k1p = Ks + (32 + r32) * ROWB;
; #pragma unroll
;   for (int d0 = 0; d0 < DQK / 16; ++d0) { const int cb = ((d0 * 16 + hi * 8) * 2) ^ sw;
;     const bf16x8 b0 = *reinterpret_cast<const bf16x8*>(k0p + cb);
;     const bf16x8 b1 = *reinterpret_cast<const bf16x8*>(k1p + cb);
;     p0 = __builtin_amdgcn_mfma_f32_32x32x16_bf16(b0, qr[d0], p0, 0, 0, 0);
;     p1 = __builtin_amdgcn_mfma_f32_32x32x16_bf16(b1, qr[d0], p1, 0, 0, 0); }
; }
.LBB0_1045:
	s_setprio 1
	v_add_u32_e32 v192, s90, v211
	v_add_u32_e32 v200, v192, v212
	ds_read_b128 v[196:199], v200
	ds_read_b128 v[228:231], v200 offset:8192
	v_add_u32_e32 v200, v192, v213
	ds_read_b128 v[232:235], v200
	ds_read_b128 v[244:247], v200 offset:8192
	s_waitcnt lgkmcnt(2)
	v_mfma_f32_32x32x16_bf16 v[128:143], v[196:199], v[160:163], 0
	v_mfma_f32_32x32x16_bf16 v[144:159], v[228:231], v[160:163], 0
	v_add_u32_e32 v200, v192, v215
	ds_read_b128 v[196:199], v200
	ds_read_b128 v[228:231], v200 offset:8192
	s_waitcnt lgkmcnt(2)
	v_mfma_f32_32x32x16_bf16 v[128:143], v[232:235], v[164:167], v[128:143]
	v_mfma_f32_32x32x16_bf16 v[144:159], v[244:247], v[164:167], v[144:159]
	v_add_u32_e32 v200, v192, v216
	ds_read_b128 v[232:235], v200
	ds_read_b128 v[244:247], v200 offset:8192
	s_waitcnt lgkmcnt(2)
	v_mfma_f32_32x32x16_bf16 v[128:143], v[196:199], v[168:171], v[128:143]
	v_mfma_f32_32x32x16_bf16 v[144:159], v[228:231], v[168:171], v[144:159]
	v_add_u32_e32 v200, v192, v217
	ds_read_b128 v[196:199], v200
	ds_read_b128 v[228:231], v200 offset:8192
	s_waitcnt lgkmcnt(2)
	v_mfma_f32_32x32x16_bf16 v[128:143], v[232:235], v[172:175], v[128:143]
	v_mfma_f32_32x32x16_bf16 v[144:159], v[244:247], v[172:175], v[144:159]
	v_add_u32_e32 v200, v192, v218
	ds_read_b128 v[232:235], v200
	ds_read_b128 v[244:247], v200 offset:8192
	s_waitcnt lgkmcnt(2)
	v_mfma_f32_32x32x16_bf16 v[128:143], v[196:199], v[176:179], v[128:143]
	v_mfma_f32_32x32x16_bf16 v[144:159], v[228:231], v[176:179], v[144:159]
	v_add_u32_e32 v200, v192, v219
	ds_read_b128 v[196:199], v200
	ds_read_b128 v[228:231], v200 offset:8192
	s_waitcnt lgkmcnt(2)
	v_mfma_f32_32x32x16_bf16 v[128:143], v[232:235], v[180:183], v[128:143]
	v_mfma_f32_32x32x16_bf16 v[144:159], v[244:247], v[180:183], v[144:159]
	v_add_u32_e32 v200, v192, v220
	ds_read_b128 v[232:235], v200
	ds_read_b128 v[244:247], v200 offset:8192
	s_waitcnt lgkmcnt(2)
	v_mfma_f32_32x32x16_bf16 v[128:143], v[196:199], v[184:187], v[128:143]
	v_mfma_f32_32x32x16_bf16 v[144:159], v[228:231], v[184:187], v[144:159]
	s_waitcnt lgkmcnt(0)
	v_mfma_f32_32x32x16_bf16 v[128:143], v[232:235], v[188:191], v[128:143]
	v_mfma_f32_32x32x16_bf16 v[144:159], v[244:247], v[188:191], v[144:159]
	s_setprio 0
	s_nop 1
	ds_read_b128 v[196:199], v222
	ds_read_b128 v[200:203], v222 offset:32
	ds_read_b128 v[224:227], v222 offset:128
	s_cmp_ge_u32 s86, s85
	s_waitcnt lgkmcnt(2)
	s_nop 3
	v_pk_mul_f32 v[196:197], v[128:129], v[196:197]
	s_waitcnt lgkmcnt(0)
	s_nop 0
	v_pk_mul_f32 v[128:129], v[144:145], v[224:225]
	v_pk_mul_f32 v[144:145], v[130:131], v[198:199]
	v_pk_mul_f32 v[130:131], v[146:147], v[226:227]
	ds_read_b128 v[224:227], v222 offset:160
	v_pk_mul_f32 v[198:199], v[132:133], v[200:201]
	v_pk_mul_f32 v[200:201], v[134:135], v[202:203]
	s_waitcnt lgkmcnt(0)
	v_pk_mul_f32 v[132:133], v[148:149], v[224:225]
	ds_read_b128 v[146:149], v222 offset:64
	ds_read_b128 v[202:205], v222 offset:192
	v_pk_mul_f32 v[134:135], v[150:151], v[226:227]
	s_waitcnt lgkmcnt(1)
	v_pk_mul_f32 v[150:151], v[136:137], v[146:147]
	s_waitcnt lgkmcnt(0)
	v_pk_mul_f32 v[146:147], v[152:153], v[202:203]
	v_pk_mul_f32 v[152:153], v[138:139], v[148:149]
	ds_read_b128 v[136:139], v222 offset:96
	ds_read_b128 v[224:227], v222 offset:224
	v_pk_mul_f32 v[148:149], v[154:155], v[204:205]
	s_waitcnt lgkmcnt(1)
	v_pk_mul_f32 v[202:203], v[140:141], v[136:137]
	s_waitcnt lgkmcnt(0)
	v_pk_mul_f32 v[154:155], v[156:157], v[224:225]
	v_pk_mul_f32 v[204:205], v[142:143], v[138:139]
	v_pk_mul_f32 v[156:157], v[158:159], v[226:227]
	s_cbranch_scc1 .LBB0_1040
	v_cmp_gt_i32_e32 vcc, 1, v223
	s_nop 1
	v_cndmask_b32_e32 v196, 0, v196, vcc
	v_cmp_gt_i32_e32 vcc, 2, v223
	s_nop 1
	v_cndmask_b32_e32 v197, 0, v197, vcc
	v_cmp_gt_i32_e32 vcc, 3, v223
	s_nop 1
	v_cndmask_b32_e32 v144, 0, v144, vcc
	v_cmp_gt_i32_e32 vcc, 4, v223
	s_nop 1
	v_cndmask_b32_e32 v145, 0, v145, vcc
	v_cmp_gt_i32_e32 vcc, 9, v223
	s_nop 1
	v_cndmask_b32_e32 v198, 0, v198, vcc
	v_cmp_gt_i32_e32 vcc, 10, v223
	s_nop 1
	v_cndmask_b32_e32 v199, 0, v199, vcc
	v_cmp_gt_i32_e32 vcc, 11, v223
	s_nop 1
	v_cndmask_b32_e32 v200, 0, v200, vcc
	v_cmp_gt_i32_e32 vcc, 12, v223
	s_nop 1
	v_cndmask_b32_e32 v201, 0, v201, vcc
	v_cmp_gt_i32_e32 vcc, 17, v223
	s_nop 1
	v_cndmask_b32_e32 v150, 0, v150, vcc
	v_cmp_gt_i32_e32 vcc, 18, v223
	s_nop 1
	v_cndmask_b32_e32 v151, 0, v151, vcc
	v_cmp_gt_i32_e32 vcc, 19, v223
	s_nop 1
	v_cndmask_b32_e32 v152, 0, v152, vcc
	v_cmp_gt_i32_e32 vcc, 20, v223
	s_nop 1
	v_cndmask_b32_e32 v153, 0, v153, vcc
	v_cmp_gt_i32_e32 vcc, 25, v223
	s_nop 1
	v_cndmask_b32_e32 v202, 0, v202, vcc
	v_cmp_gt_i32_e32 vcc, 26, v223
	s_nop 1
	v_cndmask_b32_e32 v203, 0, v203, vcc
	v_cmp_gt_i32_e32 vcc, 27, v223
	s_nop 1
	v_cndmask_b32_e32 v204, 0, v204, vcc
	v_cmp_gt_i32_e32 vcc, 28, v223
	s_nop 1
	v_cndmask_b32_e32 v205, 0, v205, vcc
	v_cmp_gt_i32_e32 vcc, 33, v223
	s_nop 1
	v_cndmask_b32_e32 v128, 0, v128, vcc
	v_cmp_gt_i32_e32 vcc, 34, v223
	s_nop 1
	v_cndmask_b32_e32 v129, 0, v129, vcc
	v_cmp_gt_i32_e32 vcc, 35, v223
	s_nop 1
	v_cndmask_b32_e32 v130, 0, v130, vcc
	v_cmp_gt_i32_e32 vcc, 36, v223
	s_nop 1
	v_cndmask_b32_e32 v131, 0, v131, vcc
	v_cmp_gt_i32_e32 vcc, 41, v223
	s_nop 1
	v_cndmask_b32_e32 v132, 0, v132, vcc
	v_cmp_gt_i32_e32 vcc, 42, v223
	s_nop 1
	v_cndmask_b32_e32 v133, 0, v133, vcc
	v_cmp_gt_i32_e32 vcc, 43, v223
	s_nop 1
	v_cndmask_b32_e32 v134, 0, v134, vcc
	v_cmp_gt_i32_e32 vcc, 44, v223
	s_nop 1
	v_cndmask_b32_e32 v135, 0, v135, vcc
	v_cmp_gt_i32_e32 vcc, 49, v223
	s_nop 1
	v_cndmask_b32_e32 v146, 0, v146, vcc
	v_cmp_gt_i32_e32 vcc, 50, v223
	s_nop 1
	v_cndmask_b32_e32 v147, 0, v147, vcc
	v_cmp_gt_i32_e32 vcc, 51, v223
	s_nop 1
	v_cndmask_b32_e32 v148, 0, v148, vcc
	v_cmp_gt_i32_e32 vcc, 52, v223
	s_nop 1
	v_cndmask_b32_e32 v149, 0, v149, vcc
	v_cmp_gt_i32_e32 vcc, 57, v223
	s_nop 1
	v_cndmask_b32_e32 v154, 0, v154, vcc
	v_cmp_gt_i32_e32 vcc, 58, v223
	s_nop 1
	v_cndmask_b32_e32 v155, 0, v155, vcc
	v_cmp_gt_i32_e32 vcc, 59, v223
	s_nop 1
	v_cndmask_b32_e32 v156, 0, v156, vcc
	v_cmp_gt_i32_e32 vcc, 60, v223
	s_nop 1
	v_cndmask_b32_e32 v157, 0, v157, vcc
	s_branch .LBB0_1040

; #define SBAR() __builtin_amdgcn_sched_barrier(0)
; template <int OFF> __device__ __forceinline__ s16x4 tr_read(int vb) { s16x4 r; asm volatile("ds_read_b64_tr_b16 %0, %1 offset:%2" : "=&v"(r) : "v"(vb), "i"(OFF) : "memory"); return r; }
; __device__ __forceinline__ void finishW(f32x16& p0, f32x16& p1, float& l_reg, bf16x8& pa0, bf16x8& pa1, bf16x8& pa2, bf16x8& pa3) {
;   float ps = 0;
; #pragma unroll
;   for (int r = 0; r < 16; ++r) ps += p0[r];
; #pragma unroll
;   for (int r = 0; r < 16; ++r) ps += p1[r];
;   { auto rr = __builtin_amdgcn_permlane32_swap(__float_as_uint(ps), __float_as_uint(ps), false, false);
;     ps = __uint_as_float(rr[0]) + __uint_as_float(rr[1]); }
;   l_reg += ps;
;   PK4(p0, 0, pa0); PK4(p0, 8, pa1); PK4(p1, 0, pa2); PK4(p1, 8, pa3);
; }
; template <int D0> __device__ __forceinline__ void pv_one_lean(f32x16& od, int vb, bf16x8 pa0, bf16x8 pa1, bf16x8 pa2, bf16x8 pa3) {
;     ...
;   { const s16x4 l0 = tr_read<v_rd_off(D0, 0, 0)>(vb), h0 = tr_read<v_rd_off(D0, 0, 1)>(vb), l1 = tr_read<v_rd_off(D0, 1, 0)>(vb), h1 = tr_read<v_rd_off(D0, 1, 1)>(vb);
;     asm volatile("s_waitcnt lgkmcnt(0)" ::: "memory"); SBAR();
;     od = __builtin_amdgcn_mfma_f32_32x32x16_bf16(pa0, PKL(l0, h0), od, 0, 0, 0); od = __builtin_amdgcn_mfma_f32_32x32x16_bf16(pa1, PKL(l1, h1), od, 0, 0, 0); }
;   SBAR();
;   { const s16x4 l2 = tr_read<v_rd_off(D0, 2, 0)>(vb), h2 = tr_read<v_rd_off(D0, 2, 1)>(vb), l3 = tr_read<v_rd_off(D0, 3, 0)>(vb), h3 = tr_read<v_rd_off(D0, 3, 1)>(vb);
;     asm volatile("s_waitcnt lgkmcnt(0)" ::: "memory"); SBAR();
;     od = __builtin_amdgcn_mfma_f32_32x32x16_bf16(pa2, PKL(l2, h2), od, 0, 0, 0); od = __builtin_amdgcn_mfma_f32_32x32x16_bf16(pa3, PKL(l3, h3), od, 0, 0, 0); }
.LBB0_1055:
	v_add_f32_e32 v132, 0, v196
	v_add_f32_e32 v132, v197, v132
	v_add_f32_e32 v132, v144, v132
	v_add_f32_e32 v132, v145, v132
	v_add_f32_e32 v132, v198, v132
	v_add_f32_e32 v132, v199, v132
	v_add_f32_e32 v132, v200, v132
	v_add_f32_e32 v132, v201, v132
	v_add_f32_e32 v132, v136, v132
	v_add_f32_e32 v132, v137, v132
	v_add_f32_e32 v132, v138, v132
	v_add_f32_e32 v132, v139, v132
	v_add_f32_e32 v132, v140, v132
	v_add_f32_e32 v132, v141, v132
	v_add_f32_e32 v132, v142, v132
	v_add_f32_e32 v132, v143, v132
	v_add_f32_e32 v132, v128, v132
	v_add_f32_e32 v132, v129, v132
	v_add_f32_e32 v132, v130, v132
	v_add_f32_e32 v132, v131, v132
	v_add_f32_e32 v132, v146, v132
	v_add_f32_e32 v132, v147, v132
	v_add_f32_e32 v132, v148, v132
	v_add_f32_e32 v132, v149, v132
	v_add_f32_e32 v132, v150, v132
	v_add_f32_e32 v132, v151, v132
	v_add_f32_e32 v132, v152, v132
	v_add_f32_e32 v132, v153, v132
	v_add_f32_e32 v132, v154, v132
	v_add_f32_e32 v132, v155, v132
	v_add_f32_e32 v132, v156, v132
	v_add_f32_e32 v132, v157, v132
	v_mov_b32_e32 v133, v132
	s_nop 1
	v_permlane32_swap_b32_e32 v132, v133
	v_add_f32_e32 v132, v132, v133
	v_add_f32_e32 v209, v209, v132
	v_cvt_pk_bf16_f32 v132, v196, v197
	v_cvt_pk_bf16_f32 v133, v144, v145
	v_cvt_pk_bf16_f32 v134, v198, v199
	v_cvt_pk_bf16_f32 v135, v200, v201
	v_cvt_pk_bf16_f32 v136, v136, v137
	v_cvt_pk_bf16_f32 v137, v138, v139
	v_cvt_pk_bf16_f32 v138, v140, v141
	v_cvt_pk_bf16_f32 v139, v142, v143
	v_cvt_pk_bf16_f32 v140, v128, v129
	v_cvt_pk_bf16_f32 v141, v130, v131
	v_cvt_pk_bf16_f32 v142, v146, v147
	v_cvt_pk_bf16_f32 v143, v148, v149
	v_cvt_pk_bf16_f32 v128, v150, v151
	v_cvt_pk_bf16_f32 v129, v152, v153
	v_cvt_pk_bf16_f32 v130, v154, v155
	v_cvt_pk_bf16_f32 v131, v156, v157
	v_permlane32_swap_b32_e32 v132, v134
	v_permlane32_swap_b32_e32 v133, v135
	v_permlane32_swap_b32_e32 v136, v138
	v_permlane32_swap_b32_e32 v137, v139
	v_permlane32_swap_b32_e32 v140, v142
	v_permlane32_swap_b32_e32 v141, v143
	v_permlane32_swap_b32_e32 v128, v130
	v_permlane32_swap_b32_e32 v129, v131
	s_setprio 1
	v_lshl_add_u32 v152, s59, 15, v217
	ds_read_b64_tr_b16 v[144:145], v152 offset:0
	ds_read_b64_tr_b16 v[146:147], v152 offset:0x800
	ds_read_b64_tr_b16 v[148:149], v152 offset:0x1000
	ds_read_b64_tr_b16 v[150:151], v152 offset:0x1800
	ds_read_b64_tr_b16 v[228:229], v152 offset:0x2000
	ds_read_b64_tr_b16 v[230:231], v152 offset:0x2800
	ds_read_b64_tr_b16 v[232:233], v152 offset:0x3000
	ds_read_b64_tr_b16 v[234:235], v152 offset:0x3800
	s_waitcnt lgkmcnt(4)
	v_mfma_f32_32x32x16_bf16 v[112:127], v[132:135], v[144:147], v[112:127]
	v_mfma_f32_32x32x16_bf16 v[112:127], v[136:139], v[148:151], v[112:127]
	ds_read_b64_tr_b16 v[144:145], v152 offset:0x200
	ds_read_b64_tr_b16 v[146:147], v152 offset:0xa00
	ds_read_b64_tr_b16 v[148:149], v152 offset:0x1200
	ds_read_b64_tr_b16 v[150:151], v152 offset:0x1a00
	s_waitcnt lgkmcnt(4)
	v_mfma_f32_32x32x16_bf16 v[112:127], v[140:143], v[228:231], v[112:127]
	v_mfma_f32_32x32x16_bf16 v[112:127], v[128:131], v[232:235], v[112:127]
	ds_read_b64_tr_b16 v[228:229], v152 offset:0x2200
	ds_read_b64_tr_b16 v[230:231], v152 offset:0x2a00
	ds_read_b64_tr_b16 v[232:233], v152 offset:0x3200
	ds_read_b64_tr_b16 v[234:235], v152 offset:0x3a00
	s_waitcnt lgkmcnt(4)
	v_mfma_f32_32x32x16_bf16 v[96:111], v[132:135], v[144:147], v[96:111]
	v_mfma_f32_32x32x16_bf16 v[96:111], v[136:139], v[148:151], v[96:111]
	ds_read_b64_tr_b16 v[144:145], v152 offset:0x400
	ds_read_b64_tr_b16 v[146:147], v152 offset:0xc00
	ds_read_b64_tr_b16 v[148:149], v152 offset:0x1400
	ds_read_b64_tr_b16 v[150:151], v152 offset:0x1c00
	s_waitcnt lgkmcnt(4)
	v_mfma_f32_32x32x16_bf16 v[96:111], v[140:143], v[228:231], v[96:111]
	v_mfma_f32_32x32x16_bf16 v[96:111], v[128:131], v[232:235], v[96:111]
	ds_read_b64_tr_b16 v[228:229], v152 offset:0x2400
	ds_read_b64_tr_b16 v[230:231], v152 offset:0x2c00
	ds_read_b64_tr_b16 v[232:233], v152 offset:0x3400
	ds_read_b64_tr_b16 v[234:235], v152 offset:0x3c00
	s_waitcnt lgkmcnt(4)
; #define SBAR() __builtin_amdgcn_sched_barrier(0)
; template <int OFF> __device__ __forceinline__ s16x4 tr_read(int vb) { s16x4 r; asm volatile("ds_read_b64_tr_b16 %0, %1 offset:%2" : "=&v"(r) : "v"(vb), "i"(OFF) : "memory"); return r; }
; #define WAIT_BAR_0() asm volatile("s_waitcnt vmcnt(0) lgkmcnt(0)\n\ts_barrier" ::: "memory")
; #define WAIT_BAR_0() asm volatile("s_waitcnt vmcnt(0) lgkmcnt(0)\n\ts_barrier" ::: "memory")
; #define WAIT_BAR_0() asm volatile("s_waitcnt vmcnt(0) lgkmcnt(0)\n\ts_barrier" ::: "memory")
; template <int D0> __device__ __forceinline__ void pv_one_lean(f32x16& od, int vb, bf16x8 pa0, bf16x8 pa1, bf16x8 pa2, bf16x8 pa3) {
;     ...
;   { const s16x4 l0 = tr_read<v_rd_off(D0, 0, 0)>(vb), h0 = tr_read<v_rd_off(D0, 0, 1)>(vb), l1 = tr_read<v_rd_off(D0, 1, 0)>(vb), h1 = tr_read<v_rd_off(D0, 1, 1)>(vb);
;     asm volatile("s_waitcnt lgkmcnt(0)" ::: "memory"); SBAR();
;     od = __builtin_amdgcn_mfma_f32_32x32x16_bf16(pa0, PKL(l0, h0), od, 0, 0, 0); od = __builtin_amdgcn_mfma_f32_32x32x16_bf16(pa1, PKL(l1, h1), od, 0, 0, 0); }
;   SBAR();
;   { const s16x4 l2 = tr_read<v_rd_off(D0, 2, 0)>(vb), h2 = tr_read<v_rd_off(D0, 2, 1)>(vb), l3 = tr_read<v_rd_off(D0, 3, 0)>(vb), h3 = tr_read<v_rd_off(D0, 3, 1)>(vb);
;     asm volatile("s_waitcnt lgkmcnt(0)" ::: "memory"); SBAR();
;     od = __builtin_amdgcn_mfma_f32_32x32x16_bf16(pa2, PKL(l2, h2), od, 0, 0, 0); od = __builtin_amdgcn_mfma_f32_32x32x16_bf16(pa3, PKL(l3, h3), od, 0, 0, 0); }
;     ...
; }
; __device__ __forceinline__ void pv_d0_lean(f32x16* o, int vb, bf16x8 pa0, bf16x8 pa1, bf16x8 pa2, bf16x8 pa3) {
;   pv_one_lean<0>(o[0], vb, pa0, pa1, pa2, pa3); SBAR(); pv_one_lean<1>(o[1], vb, pa0, pa1, pa2, pa3); SBAR(); pv_one_lean<2>(o[2], vb, pa0, pa1, pa2, pa3); SBAR(); pv_one_lean<3>(o[3], vb, pa0, pa1, pa2, pa3);
; }
; template <int MODE>
; __device__ __forceinline__ void attn_unit_ml(const AttnUnit& U, char* lds) {
;     ...
;     finishW(p0, p1, l_reg, pa0, pa1, pa2, pa3); SBAR();
;     pv_d0_lean(o, vb0 + st * SHM_V2, pa0, pa1, pa2, pa3); SBAR();
;     pv_d0_lean(o + 4, vb0 + st * SHM_V2 + 16384, pa0, pa1, pa2, pa3);
;     WAIT_BAR_0();
;   }
	v_mfma_f32_32x32x16_bf16 v[80:95], v[132:135], v[144:147], v[80:95]
	v_mfma_f32_32x32x16_bf16 v[80:95], v[136:139], v[148:151], v[80:95]
	ds_read_b64_tr_b16 v[144:145], v152 offset:0x600
	ds_read_b64_tr_b16 v[146:147], v152 offset:0xe00
	ds_read_b64_tr_b16 v[148:149], v152 offset:0x1600
	ds_read_b64_tr_b16 v[150:151], v152 offset:0x1e00
	s_waitcnt lgkmcnt(4)
	v_mfma_f32_32x32x16_bf16 v[80:95], v[140:143], v[228:231], v[80:95]
	v_mfma_f32_32x32x16_bf16 v[80:95], v[128:131], v[232:235], v[80:95]
	ds_read_b64_tr_b16 v[228:229], v152 offset:0x2600
	ds_read_b64_tr_b16 v[230:231], v152 offset:0x2e00
	ds_read_b64_tr_b16 v[232:233], v152 offset:0x3600
	ds_read_b64_tr_b16 v[234:235], v152 offset:0x3e00
	s_waitcnt lgkmcnt(4)
	v_mfma_f32_32x32x16_bf16 v[64:79], v[132:135], v[144:147], v[64:79]
	v_mfma_f32_32x32x16_bf16 v[64:79], v[136:139], v[148:151], v[64:79]
	v_add_u32_e32 v152, 0x4000, v152
	ds_read_b64_tr_b16 v[144:145], v152 offset:0
	ds_read_b64_tr_b16 v[146:147], v152 offset:0x800
	ds_read_b64_tr_b16 v[148:149], v152 offset:0x1000
	ds_read_b64_tr_b16 v[150:151], v152 offset:0x1800
	s_waitcnt lgkmcnt(4)
	v_mfma_f32_32x32x16_bf16 v[64:79], v[140:143], v[228:231], v[64:79]
	v_mfma_f32_32x32x16_bf16 v[64:79], v[128:131], v[232:235], v[64:79]
	ds_read_b64_tr_b16 v[228:229], v152 offset:0x2000
	ds_read_b64_tr_b16 v[230:231], v152 offset:0x2800
	ds_read_b64_tr_b16 v[232:233], v152 offset:0x3000
	ds_read_b64_tr_b16 v[234:235], v152 offset:0x3800
	s_waitcnt lgkmcnt(4)
	v_mfma_f32_32x32x16_bf16 v[48:63], v[132:135], v[144:147], v[48:63]
	v_mfma_f32_32x32x16_bf16 v[48:63], v[136:139], v[148:151], v[48:63]
	ds_read_b64_tr_b16 v[144:145], v152 offset:0x200
	ds_read_b64_tr_b16 v[146:147], v152 offset:0xa00
	ds_read_b64_tr_b16 v[148:149], v152 offset:0x1200
	ds_read_b64_tr_b16 v[150:151], v152 offset:0x1a00
	s_waitcnt lgkmcnt(4)
	v_mfma_f32_32x32x16_bf16 v[48:63], v[140:143], v[228:231], v[48:63]
	v_mfma_f32_32x32x16_bf16 v[48:63], v[128:131], v[232:235], v[48:63]
	ds_read_b64_tr_b16 v[228:229], v152 offset:0x2200
	ds_read_b64_tr_b16 v[230:231], v152 offset:0x2a00
	ds_read_b64_tr_b16 v[232:233], v152 offset:0x3200
	ds_read_b64_tr_b16 v[234:235], v152 offset:0x3a00
	s_waitcnt lgkmcnt(4)
	v_mfma_f32_32x32x16_bf16 v[32:47], v[132:135], v[144:147], v[32:47]
	v_mfma_f32_32x32x16_bf16 v[32:47], v[136:139], v[148:151], v[32:47]
	ds_read_b64_tr_b16 v[144:145], v152 offset:0x400
	ds_read_b64_tr_b16 v[146:147], v152 offset:0xc00
	ds_read_b64_tr_b16 v[148:149], v152 offset:0x1400
	ds_read_b64_tr_b16 v[150:151], v152 offset:0x1c00
	s_waitcnt lgkmcnt(4)
	v_mfma_f32_32x32x16_bf16 v[32:47], v[140:143], v[228:231], v[32:47]
	v_mfma_f32_32x32x16_bf16 v[32:47], v[128:131], v[232:235], v[32:47]
	ds_read_b64_tr_b16 v[228:229], v152 offset:0x2400
	ds_read_b64_tr_b16 v[230:231], v152 offset:0x2c00
	ds_read_b64_tr_b16 v[232:233], v152 offset:0x3400
	ds_read_b64_tr_b16 v[234:235], v152 offset:0x3c00
	s_waitcnt lgkmcnt(4)
	v_mfma_f32_32x32x16_bf16 v[16:31], v[132:135], v[144:147], v[16:31]
	v_mfma_f32_32x32x16_bf16 v[16:31], v[136:139], v[148:151], v[16:31]
	ds_read_b64_tr_b16 v[144:145], v152 offset:0x600
	ds_read_b64_tr_b16 v[146:147], v152 offset:0xe00
	ds_read_b64_tr_b16 v[148:149], v152 offset:0x1600
	ds_read_b64_tr_b16 v[150:151], v152 offset:0x1e00
	s_waitcnt lgkmcnt(4)
	v_mfma_f32_32x32x16_bf16 v[16:31], v[140:143], v[228:231], v[16:31]
	v_mfma_f32_32x32x16_bf16 v[16:31], v[128:131], v[232:235], v[16:31]
	ds_read_b64_tr_b16 v[228:229], v152 offset:0x2600
	ds_read_b64_tr_b16 v[230:231], v152 offset:0x2e00
	ds_read_b64_tr_b16 v[232:233], v152 offset:0x3600
	ds_read_b64_tr_b16 v[234:235], v152 offset:0x3e00
	s_waitcnt lgkmcnt(4)
	v_mfma_f32_32x32x16_bf16 v[0:15], v[132:135], v[144:147], v[0:15]
	v_mfma_f32_32x32x16_bf16 v[0:15], v[136:139], v[148:151], v[0:15]
	s_waitcnt lgkmcnt(0)
	v_mfma_f32_32x32x16_bf16 v[0:15], v[140:143], v[228:231], v[0:15]
	v_mfma_f32_32x32x16_bf16 v[0:15], v[128:131], v[232:235], v[0:15]
	s_setprio 0
	s_addk_i32 s37, 0x100
	s_add_i32 s57, s57, 64
	s_waitcnt vmcnt(0) lgkmcnt(0)
	s_barrier
	s_add_u32 s39, s39, 0x80000
	s_addc_u32 s40, s40, 0
	s_add_i32 s36, s36, 1
	v_subrev_u32_e32 v219, 64, v219
	s_cmp_eq_u32 s7, s37
	s_cbranch_scc1 .LBB0_1062

; template <int MODE> __device__ __forceinline__ void partialW2(f32x16& p0, f32x16& p1, const float* auxk, bool band, int qrel, int hi) {
; #pragma unroll
;   for (int g = 0; g < 4; ++g) { const f32x4 a = *(const f32x4*)(auxk + 8 * g + 4 * hi), b = *(const f32x4*)(auxk + 32 + 8 * g + 4 * hi);
; #pragma unroll
;     for (int e = 0; e < 4; ++e) { p0[4 * g + e] *= a[e]; p1[4 * g + e] *= b[e]; } }
;   if (band) {
; #pragma unroll
;     for (int r = 0; r < 16; ++r) { const int kvl = (r & 3) + 8 * (r >> 2);
;       const bool k0 = (MODE == 2) ? (kvl <= qrel) : (kvl >= qrel), k1 = (MODE == 2) ? (kvl + 32 <= qrel) : (kvl + 32 >= qrel);
;       p0[r] = k0 ? p0[r] : 0.f; p1[r] = k1 ? p1[r] : 0.f; }
;   }
; }
; template <int DQK> __device__ __forceinline__ void qkt_acc(f32x16& p0, f32x16& p1, const char* Ks, const bf16x8* qr, int r32, int hi) {
;   constexpr int ROWB = DQK * 2;
;   const int sw = (r32 & 7) << 4; const char* k0p = Ks + r32 * ROWB; const char* k1p = Ks + (32 + r32) * ROWB;
; #pragma unroll
;   for (int d0 = 0; d0 < DQK / 16; ++d0) { const int cb = ((d0 * 16 + hi * 8) * 2) ^ sw;
;     const bf16x8 b0 = *reinterpret_cast<const bf16x8*>(k0p + cb);
;     const bf16x8 b1 = *reinterpret_cast<const bf16x8*>(k1p + cb);
;     p0 = __builtin_amdgcn_mfma_f32_32x32x16_bf16(b0, qr[d0], p0, 0, 0, 0);
;     p1 = __builtin_amdgcn_mfma_f32_32x32x16_bf16(b1, qr[d0], p1, 0, 0, 0); }
; }
.LBB0_1060:
	s_setprio 1
	v_add_u32_e32 v192, s60, v207
	v_add_u32_e32 v200, v192, v208
	ds_read_b128 v[196:199], v200
	ds_read_b128 v[228:231], v200 offset:8192
	v_add_u32_e32 v200, v192, v210
	ds_read_b128 v[232:235], v200
	ds_read_b128 v[244:247], v200 offset:8192
	s_waitcnt lgkmcnt(2)
	v_mfma_f32_32x32x16_bf16 v[128:143], v[196:199], v[160:163], 0
	v_mfma_f32_32x32x16_bf16 v[144:159], v[228:231], v[160:163], 0
	v_add_u32_e32 v200, v192, v211
	ds_read_b128 v[196:199], v200
	ds_read_b128 v[228:231], v200 offset:8192
	s_waitcnt lgkmcnt(2)
	v_mfma_f32_32x32x16_bf16 v[128:143], v[232:235], v[164:167], v[128:143]
	v_mfma_f32_32x32x16_bf16 v[144:159], v[244:247], v[164:167], v[144:159]
	v_add_u32_e32 v200, v192, v212
	ds_read_b128 v[232:235], v200
	ds_read_b128 v[244:247], v200 offset:8192
	s_waitcnt lgkmcnt(2)
	v_mfma_f32_32x32x16_bf16 v[128:143], v[196:199], v[168:171], v[128:143]
	v_mfma_f32_32x32x16_bf16 v[144:159], v[228:231], v[168:171], v[144:159]
	v_add_u32_e32 v200, v192, v213
	ds_read_b128 v[196:199], v200
	ds_read_b128 v[228:231], v200 offset:8192
	s_waitcnt lgkmcnt(2)
	v_mfma_f32_32x32x16_bf16 v[128:143], v[232:235], v[172:175], v[128:143]
	v_mfma_f32_32x32x16_bf16 v[144:159], v[244:247], v[172:175], v[144:159]
	v_add_u32_e32 v200, v192, v214
	ds_read_b128 v[232:235], v200
	ds_read_b128 v[244:247], v200 offset:8192
	s_waitcnt lgkmcnt(2)
	v_mfma_f32_32x32x16_bf16 v[128:143], v[196:199], v[176:179], v[128:143]
	v_mfma_f32_32x32x16_bf16 v[144:159], v[228:231], v[176:179], v[144:159]
	v_add_u32_e32 v200, v192, v215
	ds_read_b128 v[196:199], v200
	ds_read_b128 v[228:231], v200 offset:8192
	s_waitcnt lgkmcnt(2)
	v_mfma_f32_32x32x16_bf16 v[128:143], v[232:235], v[180:183], v[128:143]
	v_mfma_f32_32x32x16_bf16 v[144:159], v[244:247], v[180:183], v[144:159]
	v_add_u32_e32 v200, v192, v216
	ds_read_b128 v[232:235], v200
	ds_read_b128 v[244:247], v200 offset:8192
	s_waitcnt lgkmcnt(2)
	v_mfma_f32_32x32x16_bf16 v[128:143], v[196:199], v[184:187], v[128:143]
	v_mfma_f32_32x32x16_bf16 v[144:159], v[228:231], v[184:187], v[144:159]
	s_waitcnt lgkmcnt(0)
	v_mfma_f32_32x32x16_bf16 v[128:143], v[232:235], v[188:191], v[128:143]
	v_mfma_f32_32x32x16_bf16 v[144:159], v[244:247], v[188:191], v[144:159]
	s_setprio 0
	s_nop 1
	v_add_u32_e32 v192, s37, v218
	v_add_u32_e32 v196, 0x18c00, v192
	v_add_u32_e32 v200, 0x18c80, v192
	ds_read_b128 v[196:199], v196
	ds_read_b128 v[220:223], v200
	s_cmp_le_u32 s57, s67
	s_waitcnt lgkmcnt(1)
	s_nop 1
	v_pk_mul_f32 v[196:197], v[128:129], v[196:197]
	s_waitcnt lgkmcnt(0)
	s_nop 0
	v_pk_mul_f32 v[128:129], v[144:145], v[220:221]
	v_pk_mul_f32 v[144:145], v[130:131], v[198:199]
	v_pk_mul_f32 v[130:131], v[146:147], v[222:223]
	v_add_u32_e32 v146, 0x18c20, v192
	ds_read_b128 v[198:201], v146
	v_add_u32_e32 v146, 0x18ca0, v192
	ds_read_b128 v[220:223], v146
	s_waitcnt lgkmcnt(1)
	v_pk_mul_f32 v[198:199], v[132:133], v[198:199]
	v_add_u32_e32 v132, 0x18c40, v192
	v_pk_mul_f32 v[200:201], v[134:135], v[200:201]
	ds_read_b128 v[132:135], v132
	s_waitcnt lgkmcnt(1)
	v_pk_mul_f32 v[146:147], v[148:149], v[220:221]
	v_pk_mul_f32 v[148:149], v[150:151], v[222:223]
	v_add_u32_e32 v150, 0x18cc0, v192
	ds_read_b128 v[220:223], v150
	s_waitcnt lgkmcnt(1)
	v_pk_mul_f32 v[136:137], v[136:137], v[132:133]
	v_add_u32_e32 v132, 0x18c60, v192
	v_pk_mul_f32 v[138:139], v[138:139], v[134:135]
	ds_read_b128 v[132:135], v132
	s_waitcnt lgkmcnt(1)
	v_pk_mul_f32 v[150:151], v[152:153], v[220:221]
	v_pk_mul_f32 v[152:153], v[154:155], v[222:223]
	v_add_u32_e32 v154, 0x18ce0, v192
	ds_read_b128 v[220:223], v154
	s_waitcnt lgkmcnt(1)
	v_pk_mul_f32 v[140:141], v[140:141], v[132:133]
	v_pk_mul_f32 v[142:143], v[142:143], v[134:135]
	s_waitcnt lgkmcnt(0)
	v_pk_mul_f32 v[154:155], v[156:157], v[220:221]
	v_pk_mul_f32 v[156:157], v[158:159], v[222:223]
	s_cbranch_scc1 .LBB0_1055
	v_cmp_lt_i32_e32 vcc, -1, v219
	s_nop 1
	v_cndmask_b32_e32 v196, 0, v196, vcc
	v_cmp_lt_i32_e32 vcc, 0, v219
	s_nop 1
	v_cndmask_b32_e32 v197, 0, v197, vcc
	v_cmp_lt_i32_e32 vcc, 1, v219
	s_nop 1
	v_cndmask_b32_e32 v144, 0, v144, vcc
	v_cmp_lt_i32_e32 vcc, 2, v219
	s_nop 1
	v_cndmask_b32_e32 v145, 0, v145, vcc
	v_cmp_lt_i32_e32 vcc, 7, v219
	s_nop 1
	v_cndmask_b32_e32 v198, 0, v198, vcc
	v_cmp_lt_i32_e32 vcc, 8, v219
	s_nop 1
	v_cndmask_b32_e32 v199, 0, v199, vcc
	v_cmp_lt_i32_e32 vcc, 9, v219
	s_nop 1
	v_cndmask_b32_e32 v200, 0, v200, vcc
	v_cmp_lt_i32_e32 vcc, 10, v219
	s_nop 1
	v_cndmask_b32_e32 v201, 0, v201, vcc
	v_cmp_lt_i32_e32 vcc, 15, v219
	s_nop 1
	v_cndmask_b32_e32 v136, 0, v136, vcc
	v_cmp_lt_i32_e32 vcc, 16, v219
	s_nop 1
	v_cndmask_b32_e32 v137, 0, v137, vcc
	v_cmp_lt_i32_e32 vcc, 17, v219
	s_nop 1
	v_cndmask_b32_e32 v138, 0, v138, vcc
	v_cmp_lt_i32_e32 vcc, 18, v219
	s_nop 1
	v_cndmask_b32_e32 v139, 0, v139, vcc
	v_cmp_lt_i32_e32 vcc, 23, v219
	s_nop 1
	v_cndmask_b32_e32 v140, 0, v140, vcc
	v_cmp_lt_i32_e32 vcc, 24, v219
	s_nop 1
	v_cndmask_b32_e32 v141, 0, v141, vcc
	v_cmp_lt_i32_e32 vcc, 25, v219
	s_nop 1
	v_cndmask_b32_e32 v142, 0, v142, vcc
	v_cmp_lt_i32_e32 vcc, 26, v219
	s_nop 1
	v_cndmask_b32_e32 v143, 0, v143, vcc
	v_cmp_lt_i32_e32 vcc, 31, v219
	s_nop 1
	v_cndmask_b32_e32 v128, 0, v128, vcc
	v_cmp_lt_i32_e32 vcc, 32, v219
	s_nop 1
	v_cndmask_b32_e32 v129, 0, v129, vcc
	v_cmp_lt_i32_e32 vcc, 33, v219
	s_nop 1
	v_cndmask_b32_e32 v130, 0, v130, vcc
	v_cmp_lt_i32_e32 vcc, 34, v219
	s_nop 1
	v_cndmask_b32_e32 v131, 0, v131, vcc
	v_cmp_lt_i32_e32 vcc, 39, v219
	s_nop 1
	v_cndmask_b32_e32 v146, 0, v146, vcc
	v_cmp_lt_i32_e32 vcc, 40, v219
	s_nop 1
	v_cndmask_b32_e32 v147, 0, v147, vcc
	v_cmp_lt_i32_e32 vcc, 41, v219
	s_nop 1
	v_cndmask_b32_e32 v148, 0, v148, vcc
	v_cmp_lt_i32_e32 vcc, 42, v219
	s_nop 1
	v_cndmask_b32_e32 v149, 0, v149, vcc
	v_cmp_lt_i32_e32 vcc, 47, v219
	s_nop 1
	v_cndmask_b32_e32 v150, 0, v150, vcc
	v_cmp_lt_i32_e32 vcc, 48, v219
	s_nop 1
	v_cndmask_b32_e32 v151, 0, v151, vcc
	v_cmp_lt_i32_e32 vcc, 49, v219
	s_nop 1
	v_cndmask_b32_e32 v152, 0, v152, vcc
	v_cmp_lt_i32_e32 vcc, 50, v219
	s_nop 1
	v_cndmask_b32_e32 v153, 0, v153, vcc
	v_cmp_lt_i32_e32 vcc, 55, v219
	s_nop 1
	v_cndmask_b32_e32 v154, 0, v154, vcc
	v_cmp_lt_i32_e32 vcc, 56, v219
	s_nop 1
	v_cndmask_b32_e32 v155, 0, v155, vcc
	v_cmp_lt_i32_e32 vcc, 57, v219
	s_nop 1
	v_cndmask_b32_e32 v156, 0, v156, vcc
	v_cmp_lt_i32_e32 vcc, 58, v219
	s_nop 1
	v_cndmask_b32_e32 v157, 0, v157, vcc
	s_branch .LBB0_1055
